# v13fnorm
# baseline (speedup 1.0000x reference)
; __device__ __forceinline__ int otid() { int t = threadIdx.x; asm volatile("" : "+v"(t)); return t; }
; __device__ __forceinline__ int obid() { int t = blockIdx.x; asm volatile("" : "+s"(t)); return t; }
; __device__ __forceinline__ int ogdim() { int t = gridDim.x; asm volatile("" : "+s"(t)); return t; }
; __device__ __forceinline__ void final_norm(float* __restrict__ io, const float* __restrict__ g) {
;     const int wid = otid() >> 6, lane = otid() & 63;
;     f32x4 gg[8];
; #pragma unroll
;     for (int j = 0; j < 8; ++j) gg[j] = *(const f32x4*)(g + j * 256 + lane * 4);
;     for (int row = (obid() * 8 + wid) * 2; row < NBATCH * SEQ; row += ogdim() * 16) {
;         f32x4 v[2][8];
; #pragma unroll
;         for (int q = 0; q < 2; ++q)
; #pragma unroll
;             for (int j = 0; j < 8; ++j) v[q][j] = *(const f32x4*)(io + (size_t)(row + q) * DM + j * 256 + lane * 4);
.LBB0_883:
	v_readlane_b32 s2, v253, 11
	v_readlane_b32 s3, v253, 12
	v_mov_b32_e32 v0, v199
	v_readlane_b32 s0, v253, 0
	v_ashrrev_i32_e32 v0, 5, v0
	v_and_b32_e32 v0, -2, v0
	v_lshl_add_u32 v88, s0, 4, v0
	s_mov_b32 s0, 0x8000
	v_cmp_gt_i32_e32 vcc, s0, v88
	s_and_saveexec_b64 s[0:1], vcc
	s_cbranch_execz .LBB0_886
	s_load_dwordx4 s[4:7], s[2:3], 0x80
	v_and_b32_e32 v170, 63, v199
	v_lshlrev_b32_e32 v171, 4, v170
	v_readfirstlane_b32 s8, v88
	s_load_dword s9, s[2:3], 0x98
	v_xor_b32_e32 v172, 32, v170
	v_lshlrev_b32_e32 v172, 2, v172
	v_xor_b32_e32 v173, 16, v170
	v_lshlrev_b32_e32 v173, 2, v173
	v_xor_b32_e32 v174, 8, v170
	v_lshlrev_b32_e32 v174, 2, v174
	v_xor_b32_e32 v175, 4, v170
	v_lshlrev_b32_e32 v175, 2, v175
	v_xor_b32_e32 v176, 2, v170
	v_lshlrev_b32_e32 v176, 2, v176
	v_xor_b32_e32 v177, 1, v170
	v_lshlrev_b32_e32 v177, 2, v177
	v_mov_b32_e32 v160, 0x358637bd
	s_waitcnt lgkmcnt(0)
	s_lshl_b32 s9, s9, 4
	s_add_u32 s10, s4, 0x1000
	s_addc_u32 s11, s5, 0
	global_load_dwordx4 v[128:131], v171, s[4:5]
	global_load_dwordx4 v[132:135], v171, s[4:5] offset:1024
	global_load_dwordx4 v[136:139], v171, s[4:5] offset:2048
	global_load_dwordx4 v[140:143], v171, s[4:5] offset:3072
	global_load_dwordx4 v[144:147], v171, s[10:11]
	global_load_dwordx4 v[148:151], v171, s[10:11] offset:1024
	global_load_dwordx4 v[152:155], v171, s[10:11] offset:2048
	global_load_dwordx4 v[156:159], v171, s[10:11] offset:3072
	s_lshl_b32 s29, s8, 13
	s_add_u32 s12, s6, s29
	s_addc_u32 s13, s7, 0
	s_add_u32 s14, s12, 0x1000
	s_addc_u32 s15, s13, 0
	s_add_u32 s16, s12, 0x2000
	s_addc_u32 s17, s13, 0
	s_add_u32 s18, s12, 0x3000
	s_addc_u32 s19, s13, 0
	global_load_dwordx4 v[0:3], v171, s[12:13]
	global_load_dwordx4 v[4:7], v171, s[12:13] offset:1024
	global_load_dwordx4 v[8:11], v171, s[12:13] offset:2048
	global_load_dwordx4 v[12:15], v171, s[12:13] offset:3072
	global_load_dwordx4 v[16:19], v171, s[14:15]
	global_load_dwordx4 v[20:23], v171, s[14:15] offset:1024
	global_load_dwordx4 v[24:27], v171, s[14:15] offset:2048
	global_load_dwordx4 v[28:31], v171, s[14:15] offset:3072
	global_load_dwordx4 v[32:35], v171, s[16:17]
	global_load_dwordx4 v[36:39], v171, s[16:17] offset:1024
	global_load_dwordx4 v[40:43], v171, s[16:17] offset:2048
	global_load_dwordx4 v[44:47], v171, s[16:17] offset:3072
	global_load_dwordx4 v[48:51], v171, s[18:19]
	global_load_dwordx4 v[52:55], v171, s[18:19] offset:1024
	global_load_dwordx4 v[56:59], v171, s[18:19] offset:2048
	global_load_dwordx4 v[60:63], v171, s[18:19] offset:3072
	s_add_u32 s28, s8, s9
	s_cmp_lt_u32 s28, 0x8000
	s_cselect_b32 s30, 1, 0
	s_cbranch_scc0 .Lmy_fn_nonext_i0
	s_lshl_b32 s29, s28, 13
	s_add_u32 s20, s6, s29
	s_addc_u32 s21, s7, 0
	s_add_u32 s22, s20, 0x1000
	s_addc_u32 s23, s21, 0
	s_add_u32 s24, s20, 0x2000
	s_addc_u32 s25, s21, 0
	s_add_u32 s26, s20, 0x3000
	s_addc_u32 s27, s21, 0
	global_load_dwordx4 v[64:67], v171, s[20:21]
	global_load_dwordx4 v[68:71], v171, s[20:21] offset:1024
	global_load_dwordx4 v[72:75], v171, s[20:21] offset:2048
	global_load_dwordx4 v[76:79], v171, s[20:21] offset:3072
	global_load_dwordx4 v[80:83], v171, s[22:23]
	global_load_dwordx4 v[84:87], v171, s[22:23] offset:1024
	global_load_dwordx4 v[88:91], v171, s[22:23] offset:2048
	global_load_dwordx4 v[92:95], v171, s[22:23] offset:3072
	global_load_dwordx4 v[96:99], v171, s[24:25]
	global_load_dwordx4 v[100:103], v171, s[24:25] offset:1024
	global_load_dwordx4 v[104:107], v171, s[24:25] offset:2048
	global_load_dwordx4 v[108:111], v171, s[24:25] offset:3072
	global_load_dwordx4 v[112:115], v171, s[26:27]
	global_load_dwordx4 v[116:119], v171, s[26:27] offset:1024
	global_load_dwordx4 v[120:123], v171, s[26:27] offset:2048
	global_load_dwordx4 v[124:127], v171, s[26:27] offset:3072
	s_waitcnt vmcnt(16)
	s_branch .Lmy_fn_proc_i0

; __device__ __forceinline__ void final_norm(float* __restrict__ io, const float* __restrict__ g) {
;     ...
;         for (int q = 0; q < 2; ++q) { float ss = 0.f;
; #pragma unroll
;             for (int j = 0; j < 8; ++j) ss += v[q][j][0] * v[q][j][0] + v[q][j][1] * v[q][j][1] + v[q][j][2] * v[q][j][2] + v[q][j][3] * v[q][j][3];
;             ss = wave_sum(ss); const float rs = rsqrtf(ss * (1.f / DM) + EPS);
; #pragma unroll
;             for (int j = 0; j < 8; ++j) *(f32x4*)(io + (size_t)(row + q) * DM + j * 256 + lane * 4) = v[q][j] * rs * gg[j]; }
.Lmy_fn_proc_i0:
	v_mul_f32_e32 v161, v0, v0
	v_fmac_f32_e32 v161, v1, v1
	v_fmac_f32_e32 v161, v2, v2
	v_fmac_f32_e32 v161, v3, v3
	v_fmac_f32_e32 v161, v4, v4
	v_fmac_f32_e32 v161, v5, v5
	v_fmac_f32_e32 v161, v6, v6
	v_fmac_f32_e32 v161, v7, v7
	v_fmac_f32_e32 v161, v8, v8
	v_fmac_f32_e32 v161, v9, v9
	v_fmac_f32_e32 v161, v10, v10
	v_fmac_f32_e32 v161, v11, v11
	v_fmac_f32_e32 v161, v12, v12
	v_fmac_f32_e32 v161, v13, v13
	v_fmac_f32_e32 v161, v14, v14
	v_fmac_f32_e32 v161, v15, v15
	v_fmac_f32_e32 v161, v16, v16
	v_fmac_f32_e32 v161, v17, v17
	v_fmac_f32_e32 v161, v18, v18
	v_fmac_f32_e32 v161, v19, v19
	v_fmac_f32_e32 v161, v20, v20
	v_fmac_f32_e32 v161, v21, v21
	v_fmac_f32_e32 v161, v22, v22
	v_fmac_f32_e32 v161, v23, v23
	v_fmac_f32_e32 v161, v24, v24
	v_fmac_f32_e32 v161, v25, v25
	v_fmac_f32_e32 v161, v26, v26
	v_fmac_f32_e32 v161, v27, v27
	v_fmac_f32_e32 v161, v28, v28
	v_fmac_f32_e32 v161, v29, v29
	v_fmac_f32_e32 v161, v30, v30
	v_fmac_f32_e32 v161, v31, v31
	v_mul_f32_e32 v162, v32, v32
	v_fmac_f32_e32 v162, v33, v33
	v_fmac_f32_e32 v162, v34, v34
	v_fmac_f32_e32 v162, v35, v35
	v_fmac_f32_e32 v162, v36, v36
	v_fmac_f32_e32 v162, v37, v37
	v_fmac_f32_e32 v162, v38, v38
	v_fmac_f32_e32 v162, v39, v39
	v_fmac_f32_e32 v162, v40, v40
	v_fmac_f32_e32 v162, v41, v41
	v_fmac_f32_e32 v162, v42, v42
	v_fmac_f32_e32 v162, v43, v43
	v_fmac_f32_e32 v162, v44, v44
	v_fmac_f32_e32 v162, v45, v45
	v_fmac_f32_e32 v162, v46, v46
	v_fmac_f32_e32 v162, v47, v47
	v_fmac_f32_e32 v162, v48, v48
	v_fmac_f32_e32 v162, v49, v49
	v_fmac_f32_e32 v162, v50, v50
	v_fmac_f32_e32 v162, v51, v51
	v_fmac_f32_e32 v162, v52, v52
	v_fmac_f32_e32 v162, v53, v53
	v_fmac_f32_e32 v162, v54, v54
	v_fmac_f32_e32 v162, v55, v55
	v_fmac_f32_e32 v162, v56, v56
	v_fmac_f32_e32 v162, v57, v57
	v_fmac_f32_e32 v162, v58, v58
	v_fmac_f32_e32 v162, v59, v59
	v_fmac_f32_e32 v162, v60, v60
	v_fmac_f32_e32 v162, v61, v61
	v_fmac_f32_e32 v162, v62, v62
	v_fmac_f32_e32 v162, v63, v63
	ds_bpermute_b32 v163, v172, v161
	ds_bpermute_b32 v164, v172, v162
	s_waitcnt lgkmcnt(0)
	v_add_f32_e32 v161, v161, v163
	v_add_f32_e32 v162, v162, v164
	ds_bpermute_b32 v163, v173, v161
	ds_bpermute_b32 v164, v173, v162
	s_waitcnt lgkmcnt(0)
	v_add_f32_e32 v161, v161, v163
	v_add_f32_e32 v162, v162, v164
	ds_bpermute_b32 v163, v174, v161
	ds_bpermute_b32 v164, v174, v162
	s_waitcnt lgkmcnt(0)
	v_add_f32_e32 v161, v161, v163
	v_add_f32_e32 v162, v162, v164
	ds_bpermute_b32 v163, v175, v161
	ds_bpermute_b32 v164, v175, v162
	s_waitcnt lgkmcnt(0)
	v_add_f32_e32 v161, v161, v163
	v_add_f32_e32 v162, v162, v164
	ds_bpermute_b32 v163, v176, v161
	ds_bpermute_b32 v164, v176, v162
	s_waitcnt lgkmcnt(0)
	v_add_f32_e32 v161, v161, v163
	v_add_f32_e32 v162, v162, v164
	ds_bpermute_b32 v163, v177, v161
	ds_bpermute_b32 v164, v177, v162
	s_waitcnt lgkmcnt(0)
	v_add_f32_e32 v161, v161, v163
	v_add_f32_e32 v162, v162, v164
	v_fmamk_f32 v161, v161, 0x3a000000, v160
	v_fmamk_f32 v162, v162, 0x3a000000, v160
	v_rsq_f32_e32 v161, v161
	v_rsq_f32_e32 v162, v162
	s_nop 1
	v_mul_f32_e32 v0, v0, v161
	v_mul_f32_e32 v0, v0, v128
	v_mul_f32_e32 v1, v1, v161
	v_mul_f32_e32 v1, v1, v129
	v_mul_f32_e32 v2, v2, v161
	v_mul_f32_e32 v2, v2, v130
	v_mul_f32_e32 v3, v3, v161
	v_mul_f32_e32 v3, v3, v131
	v_mul_f32_e32 v4, v4, v161
	v_mul_f32_e32 v4, v4, v132
	v_mul_f32_e32 v5, v5, v161
	v_mul_f32_e32 v5, v5, v133
	v_mul_f32_e32 v6, v6, v161
	v_mul_f32_e32 v6, v6, v134
	v_mul_f32_e32 v7, v7, v161
	v_mul_f32_e32 v7, v7, v135
	v_mul_f32_e32 v8, v8, v161
	v_mul_f32_e32 v8, v8, v136
	v_mul_f32_e32 v9, v9, v161
	v_mul_f32_e32 v9, v9, v137
	v_mul_f32_e32 v10, v10, v161
	v_mul_f32_e32 v10, v10, v138
	v_mul_f32_e32 v11, v11, v161
	v_mul_f32_e32 v11, v11, v139
	v_mul_f32_e32 v12, v12, v161
	v_mul_f32_e32 v12, v12, v140
	v_mul_f32_e32 v13, v13, v161
	v_mul_f32_e32 v13, v13, v141
	v_mul_f32_e32 v14, v14, v161
	v_mul_f32_e32 v14, v14, v142
	v_mul_f32_e32 v15, v15, v161
	v_mul_f32_e32 v15, v15, v143
	v_mul_f32_e32 v16, v16, v161
	v_mul_f32_e32 v16, v16, v144
	v_mul_f32_e32 v17, v17, v161
	v_mul_f32_e32 v17, v17, v145
	v_mul_f32_e32 v18, v18, v161
	v_mul_f32_e32 v18, v18, v146
	v_mul_f32_e32 v19, v19, v161
	v_mul_f32_e32 v19, v19, v147
	v_mul_f32_e32 v20, v20, v161
	v_mul_f32_e32 v20, v20, v148
	v_mul_f32_e32 v21, v21, v161
	v_mul_f32_e32 v21, v21, v149
	v_mul_f32_e32 v22, v22, v161
	v_mul_f32_e32 v22, v22, v150
	v_mul_f32_e32 v23, v23, v161
	v_mul_f32_e32 v23, v23, v151
	v_mul_f32_e32 v24, v24, v161
	v_mul_f32_e32 v24, v24, v152
	v_mul_f32_e32 v25, v25, v161
	v_mul_f32_e32 v25, v25, v153
	v_mul_f32_e32 v26, v26, v161
	v_mul_f32_e32 v26, v26, v154
	v_mul_f32_e32 v27, v27, v161
	v_mul_f32_e32 v27, v27, v155
	v_mul_f32_e32 v28, v28, v161
	v_mul_f32_e32 v28, v28, v156
	v_mul_f32_e32 v29, v29, v161
	v_mul_f32_e32 v29, v29, v157
	v_mul_f32_e32 v30, v30, v161
	v_mul_f32_e32 v30, v30, v158
	v_mul_f32_e32 v31, v31, v161
	v_mul_f32_e32 v31, v31, v159
	v_mul_f32_e32 v32, v32, v162
	v_mul_f32_e32 v32, v32, v128
	v_mul_f32_e32 v33, v33, v162
	v_mul_f32_e32 v33, v33, v129
	v_mul_f32_e32 v34, v34, v162
	v_mul_f32_e32 v34, v34, v130
	v_mul_f32_e32 v35, v35, v162
	v_mul_f32_e32 v35, v35, v131
	v_mul_f32_e32 v36, v36, v162
	v_mul_f32_e32 v36, v36, v132
	v_mul_f32_e32 v37, v37, v162
	v_mul_f32_e32 v37, v37, v133
	v_mul_f32_e32 v38, v38, v162
	v_mul_f32_e32 v38, v38, v134
	v_mul_f32_e32 v39, v39, v162
	v_mul_f32_e32 v39, v39, v135
	v_mul_f32_e32 v40, v40, v162
	v_mul_f32_e32 v40, v40, v136
	v_mul_f32_e32 v41, v41, v162
	v_mul_f32_e32 v41, v41, v137
	v_mul_f32_e32 v42, v42, v162
	v_mul_f32_e32 v42, v42, v138
	v_mul_f32_e32 v43, v43, v162
	v_mul_f32_e32 v43, v43, v139
; __device__ __forceinline__ int obid() { int t = blockIdx.x; asm volatile("" : "+s"(t)); return t; }
; __device__ __forceinline__ int ogdim() { int t = gridDim.x; asm volatile("" : "+s"(t)); return t; }
; __device__ __forceinline__ void final_norm(float* __restrict__ io, const float* __restrict__ g) {
;     ...
;     for (int row = (obid() * 8 + wid) * 2; row < NBATCH * SEQ; row += ogdim() * 16) {
;         f32x4 v[2][8];
; #pragma unroll
;         for (int q = 0; q < 2; ++q)
; #pragma unroll
;             for (int j = 0; j < 8; ++j) v[q][j] = *(const f32x4*)(io + (size_t)(row + q) * DM + j * 256 + lane * 4);
; #pragma unroll
;         for (int q = 0; q < 2; ++q) { float ss = 0.f;
; #pragma unroll
;             for (int j = 0; j < 8; ++j) ss += v[q][j][0] * v[q][j][0] + v[q][j][1] * v[q][j][1] + v[q][j][2] * v[q][j][2] + v[q][j][3] * v[q][j][3];
;             ss = wave_sum(ss); const float rs = rsqrtf(ss * (1.f / DM) + EPS);
; #pragma unroll
;             for (int j = 0; j < 8; ++j) *(f32x4*)(io + (size_t)(row + q) * DM + j * 256 + lane * 4) = v[q][j] * rs * gg[j]; }
	v_mul_f32_e32 v44, v44, v162
	v_mul_f32_e32 v44, v44, v140
	v_mul_f32_e32 v45, v45, v162
	v_mul_f32_e32 v45, v45, v141
	v_mul_f32_e32 v46, v46, v162
	v_mul_f32_e32 v46, v46, v142
	v_mul_f32_e32 v47, v47, v162
	v_mul_f32_e32 v47, v47, v143
	v_mul_f32_e32 v48, v48, v162
	v_mul_f32_e32 v48, v48, v144
	v_mul_f32_e32 v49, v49, v162
	v_mul_f32_e32 v49, v49, v145
	v_mul_f32_e32 v50, v50, v162
	v_mul_f32_e32 v50, v50, v146
	v_mul_f32_e32 v51, v51, v162
	v_mul_f32_e32 v51, v51, v147
	v_mul_f32_e32 v52, v52, v162
	v_mul_f32_e32 v52, v52, v148
	v_mul_f32_e32 v53, v53, v162
	v_mul_f32_e32 v53, v53, v149
	v_mul_f32_e32 v54, v54, v162
	v_mul_f32_e32 v54, v54, v150
	v_mul_f32_e32 v55, v55, v162
	v_mul_f32_e32 v55, v55, v151
	v_mul_f32_e32 v56, v56, v162
	v_mul_f32_e32 v56, v56, v152
	v_mul_f32_e32 v57, v57, v162
	v_mul_f32_e32 v57, v57, v153
	v_mul_f32_e32 v58, v58, v162
	v_mul_f32_e32 v58, v58, v154
	v_mul_f32_e32 v59, v59, v162
	v_mul_f32_e32 v59, v59, v155
	v_mul_f32_e32 v60, v60, v162
	v_mul_f32_e32 v60, v60, v156
	v_mul_f32_e32 v61, v61, v162
	v_mul_f32_e32 v61, v61, v157
	v_mul_f32_e32 v62, v62, v162
	v_mul_f32_e32 v62, v62, v158
	v_mul_f32_e32 v63, v63, v162
	v_mul_f32_e32 v63, v63, v159
	global_store_dwordx4 v171, v[0:3], s[12:13]
	global_store_dwordx4 v171, v[4:7], s[12:13] offset:1024
	global_store_dwordx4 v171, v[8:11], s[12:13] offset:2048
	global_store_dwordx4 v171, v[12:15], s[12:13] offset:3072
	global_store_dwordx4 v171, v[16:19], s[14:15]
	global_store_dwordx4 v171, v[20:23], s[14:15] offset:1024
	global_store_dwordx4 v171, v[24:27], s[14:15] offset:2048
	global_store_dwordx4 v171, v[28:31], s[14:15] offset:3072
	global_store_dwordx4 v171, v[32:35], s[16:17]
	global_store_dwordx4 v171, v[36:39], s[16:17] offset:1024
	global_store_dwordx4 v171, v[40:43], s[16:17] offset:2048
	global_store_dwordx4 v171, v[44:47], s[16:17] offset:3072
	global_store_dwordx4 v171, v[48:51], s[18:19]
	global_store_dwordx4 v171, v[52:55], s[18:19] offset:1024
	global_store_dwordx4 v171, v[56:59], s[18:19] offset:2048
	global_store_dwordx4 v171, v[60:63], s[18:19] offset:3072
	s_cmp_eq_u32 s30, 0
	s_cbranch_scc1 .LBB0_886
	s_mov_b32 s8, s28
	s_mov_b64 s[12:13], s[20:21]
	s_mov_b64 s[14:15], s[22:23]
	s_mov_b64 s[16:17], s[24:25]
	s_mov_b64 s[18:19], s[26:27]
.Lmy_fn_loop:
	s_add_u32 s28, s8, s9
	s_cmp_lt_u32 s28, 0x8000
	s_cselect_b32 s30, 1, 0
	s_cbranch_scc0 .Lmy_fn_nonext_ib
	s_lshl_b32 s29, s28, 13
	s_add_u32 s20, s6, s29
	s_addc_u32 s21, s7, 0
	s_add_u32 s22, s20, 0x1000
	s_addc_u32 s23, s21, 0
	s_add_u32 s24, s20, 0x2000
	s_addc_u32 s25, s21, 0
	s_add_u32 s26, s20, 0x3000
	s_addc_u32 s27, s21, 0
	global_load_dwordx4 v[0:3], v171, s[20:21]
	global_load_dwordx4 v[4:7], v171, s[20:21] offset:1024
	global_load_dwordx4 v[8:11], v171, s[20:21] offset:2048
	global_load_dwordx4 v[12:15], v171, s[20:21] offset:3072
	global_load_dwordx4 v[16:19], v171, s[22:23]
	global_load_dwordx4 v[20:23], v171, s[22:23] offset:1024
	global_load_dwordx4 v[24:27], v171, s[22:23] offset:2048
	global_load_dwordx4 v[28:31], v171, s[22:23] offset:3072
	global_load_dwordx4 v[32:35], v171, s[24:25]
	global_load_dwordx4 v[36:39], v171, s[24:25] offset:1024
	global_load_dwordx4 v[40:43], v171, s[24:25] offset:2048
	global_load_dwordx4 v[44:47], v171, s[24:25] offset:3072
	global_load_dwordx4 v[48:51], v171, s[26:27]
	global_load_dwordx4 v[52:55], v171, s[26:27] offset:1024
	global_load_dwordx4 v[56:59], v171, s[26:27] offset:2048
	global_load_dwordx4 v[60:63], v171, s[26:27] offset:3072
	s_waitcnt vmcnt(32)
	s_branch .Lmy_fn_proc_ib
.Lmy_fn_nonext_ib:
	s_waitcnt vmcnt(16)
.Lmy_fn_proc_ib:
	v_mul_f32_e32 v161, v64, v64
	v_fmac_f32_e32 v161, v65, v65
	v_fmac_f32_e32 v161, v66, v66
	v_fmac_f32_e32 v161, v67, v67
	v_fmac_f32_e32 v161, v68, v68
	v_fmac_f32_e32 v161, v69, v69
	v_fmac_f32_e32 v161, v70, v70
	v_fmac_f32_e32 v161, v71, v71
	v_fmac_f32_e32 v161, v72, v72
	v_fmac_f32_e32 v161, v73, v73
	v_fmac_f32_e32 v161, v74, v74
	v_fmac_f32_e32 v161, v75, v75
	v_fmac_f32_e32 v161, v76, v76
	v_fmac_f32_e32 v161, v77, v77
	v_fmac_f32_e32 v161, v78, v78
	v_fmac_f32_e32 v161, v79, v79
	v_fmac_f32_e32 v161, v80, v80
	v_fmac_f32_e32 v161, v81, v81
	v_fmac_f32_e32 v161, v82, v82
	v_fmac_f32_e32 v161, v83, v83
	v_fmac_f32_e32 v161, v84, v84
	v_fmac_f32_e32 v161, v85, v85
	v_fmac_f32_e32 v161, v86, v86
	v_fmac_f32_e32 v161, v87, v87
	v_fmac_f32_e32 v161, v88, v88
	v_fmac_f32_e32 v161, v89, v89
	v_fmac_f32_e32 v161, v90, v90
	v_fmac_f32_e32 v161, v91, v91
	v_fmac_f32_e32 v161, v92, v92
	v_fmac_f32_e32 v161, v93, v93
	v_fmac_f32_e32 v161, v94, v94
	v_fmac_f32_e32 v161, v95, v95
	v_mul_f32_e32 v162, v96, v96
	v_fmac_f32_e32 v162, v97, v97
	v_fmac_f32_e32 v162, v98, v98
	v_fmac_f32_e32 v162, v99, v99
	v_fmac_f32_e32 v162, v100, v100
	v_fmac_f32_e32 v162, v101, v101
	v_fmac_f32_e32 v162, v102, v102
	v_fmac_f32_e32 v162, v103, v103
	v_fmac_f32_e32 v162, v104, v104
	v_fmac_f32_e32 v162, v105, v105
	v_fmac_f32_e32 v162, v106, v106
	v_fmac_f32_e32 v162, v107, v107
	v_fmac_f32_e32 v162, v108, v108
	v_fmac_f32_e32 v162, v109, v109
	v_fmac_f32_e32 v162, v110, v110
	v_fmac_f32_e32 v162, v111, v111
	v_fmac_f32_e32 v162, v112, v112
	v_fmac_f32_e32 v162, v113, v113
	v_fmac_f32_e32 v162, v114, v114
	v_fmac_f32_e32 v162, v115, v115
	v_fmac_f32_e32 v162, v116, v116
	v_fmac_f32_e32 v162, v117, v117
	v_fmac_f32_e32 v162, v118, v118
	v_fmac_f32_e32 v162, v119, v119
	v_fmac_f32_e32 v162, v120, v120
	v_fmac_f32_e32 v162, v121, v121
	v_fmac_f32_e32 v162, v122, v122
	v_fmac_f32_e32 v162, v123, v123
	v_fmac_f32_e32 v162, v124, v124
	v_fmac_f32_e32 v162, v125, v125
	v_fmac_f32_e32 v162, v126, v126
	v_fmac_f32_e32 v162, v127, v127
	ds_bpermute_b32 v163, v172, v161
	ds_bpermute_b32 v164, v172, v162
	s_waitcnt lgkmcnt(0)
; __device__ __forceinline__ void final_norm(float* __restrict__ io, const float* __restrict__ g) {
;     ...
;         for (int q = 0; q < 2; ++q) { float ss = 0.f;
; #pragma unroll
;             for (int j = 0; j < 8; ++j) ss += v[q][j][0] * v[q][j][0] + v[q][j][1] * v[q][j][1] + v[q][j][2] * v[q][j][2] + v[q][j][3] * v[q][j][3];
;             ss = wave_sum(ss); const float rs = rsqrtf(ss * (1.f / DM) + EPS);
; #pragma unroll
;             for (int j = 0; j < 8; ++j) *(f32x4*)(io + (size_t)(row + q) * DM + j * 256 + lane * 4) = v[q][j] * rs * gg[j]; }
	v_add_f32_e32 v161, v161, v163
	v_add_f32_e32 v162, v162, v164
	ds_bpermute_b32 v163, v173, v161
	ds_bpermute_b32 v164, v173, v162
	s_waitcnt lgkmcnt(0)
	v_add_f32_e32 v161, v161, v163
	v_add_f32_e32 v162, v162, v164
	ds_bpermute_b32 v163, v174, v161
	ds_bpermute_b32 v164, v174, v162
	s_waitcnt lgkmcnt(0)
	v_add_f32_e32 v161, v161, v163
	v_add_f32_e32 v162, v162, v164
	ds_bpermute_b32 v163, v175, v161
	ds_bpermute_b32 v164, v175, v162
	s_waitcnt lgkmcnt(0)
	v_add_f32_e32 v161, v161, v163
	v_add_f32_e32 v162, v162, v164
	ds_bpermute_b32 v163, v176, v161
	ds_bpermute_b32 v164, v176, v162
	s_waitcnt lgkmcnt(0)
	v_add_f32_e32 v161, v161, v163
	v_add_f32_e32 v162, v162, v164
	ds_bpermute_b32 v163, v177, v161
	ds_bpermute_b32 v164, v177, v162
	s_waitcnt lgkmcnt(0)
	v_add_f32_e32 v161, v161, v163
	v_add_f32_e32 v162, v162, v164
	v_fmamk_f32 v161, v161, 0x3a000000, v160
	v_fmamk_f32 v162, v162, 0x3a000000, v160
	v_rsq_f32_e32 v161, v161
	v_rsq_f32_e32 v162, v162
	s_nop 1
	v_mul_f32_e32 v64, v64, v161
	v_mul_f32_e32 v64, v64, v128
	v_mul_f32_e32 v65, v65, v161
	v_mul_f32_e32 v65, v65, v129
	v_mul_f32_e32 v66, v66, v161
	v_mul_f32_e32 v66, v66, v130
	v_mul_f32_e32 v67, v67, v161
	v_mul_f32_e32 v67, v67, v131
	v_mul_f32_e32 v68, v68, v161
	v_mul_f32_e32 v68, v68, v132
	v_mul_f32_e32 v69, v69, v161
	v_mul_f32_e32 v69, v69, v133
	v_mul_f32_e32 v70, v70, v161
	v_mul_f32_e32 v70, v70, v134
	v_mul_f32_e32 v71, v71, v161
	v_mul_f32_e32 v71, v71, v135
	v_mul_f32_e32 v72, v72, v161
	v_mul_f32_e32 v72, v72, v136
	v_mul_f32_e32 v73, v73, v161
	v_mul_f32_e32 v73, v73, v137
	v_mul_f32_e32 v74, v74, v161
	v_mul_f32_e32 v74, v74, v138
	v_mul_f32_e32 v75, v75, v161
	v_mul_f32_e32 v75, v75, v139
	v_mul_f32_e32 v76, v76, v161
	v_mul_f32_e32 v76, v76, v140
	v_mul_f32_e32 v77, v77, v161
	v_mul_f32_e32 v77, v77, v141
	v_mul_f32_e32 v78, v78, v161
	v_mul_f32_e32 v78, v78, v142
	v_mul_f32_e32 v79, v79, v161
	v_mul_f32_e32 v79, v79, v143
	v_mul_f32_e32 v80, v80, v161
	v_mul_f32_e32 v80, v80, v144
	v_mul_f32_e32 v81, v81, v161
	v_mul_f32_e32 v81, v81, v145
	v_mul_f32_e32 v82, v82, v161
	v_mul_f32_e32 v82, v82, v146
	v_mul_f32_e32 v83, v83, v161
	v_mul_f32_e32 v83, v83, v147
	v_mul_f32_e32 v84, v84, v161
	v_mul_f32_e32 v84, v84, v148
	v_mul_f32_e32 v85, v85, v161
	v_mul_f32_e32 v85, v85, v149
	v_mul_f32_e32 v86, v86, v161
	v_mul_f32_e32 v86, v86, v150
	v_mul_f32_e32 v87, v87, v161
	v_mul_f32_e32 v87, v87, v151
	v_mul_f32_e32 v88, v88, v161
	v_mul_f32_e32 v88, v88, v152
	v_mul_f32_e32 v89, v89, v161
	v_mul_f32_e32 v89, v89, v153
	v_mul_f32_e32 v90, v90, v161
	v_mul_f32_e32 v90, v90, v154
	v_mul_f32_e32 v91, v91, v161
	v_mul_f32_e32 v91, v91, v155
	v_mul_f32_e32 v92, v92, v161
	v_mul_f32_e32 v92, v92, v156
	v_mul_f32_e32 v93, v93, v161
	v_mul_f32_e32 v93, v93, v157
	v_mul_f32_e32 v94, v94, v161
	v_mul_f32_e32 v94, v94, v158
	v_mul_f32_e32 v95, v95, v161
	v_mul_f32_e32 v95, v95, v159
	v_mul_f32_e32 v96, v96, v162
	v_mul_f32_e32 v96, v96, v128
	v_mul_f32_e32 v97, v97, v162
	v_mul_f32_e32 v97, v97, v129
	v_mul_f32_e32 v98, v98, v162
	v_mul_f32_e32 v98, v98, v130
	v_mul_f32_e32 v99, v99, v162
	v_mul_f32_e32 v99, v99, v131
	v_mul_f32_e32 v100, v100, v162
	v_mul_f32_e32 v100, v100, v132
	v_mul_f32_e32 v101, v101, v162
	v_mul_f32_e32 v101, v101, v133
	v_mul_f32_e32 v102, v102, v162
	v_mul_f32_e32 v102, v102, v134
	v_mul_f32_e32 v103, v103, v162
	v_mul_f32_e32 v103, v103, v135
	v_mul_f32_e32 v104, v104, v162
	v_mul_f32_e32 v104, v104, v136
	v_mul_f32_e32 v105, v105, v162
	v_mul_f32_e32 v105, v105, v137
	v_mul_f32_e32 v106, v106, v162
	v_mul_f32_e32 v106, v106, v138
	v_mul_f32_e32 v107, v107, v162
	v_mul_f32_e32 v107, v107, v139
	v_mul_f32_e32 v108, v108, v162
	v_mul_f32_e32 v108, v108, v140
	v_mul_f32_e32 v109, v109, v162
	v_mul_f32_e32 v109, v109, v141
	v_mul_f32_e32 v110, v110, v162
	v_mul_f32_e32 v110, v110, v142
	v_mul_f32_e32 v111, v111, v162
	v_mul_f32_e32 v111, v111, v143
	v_mul_f32_e32 v112, v112, v162
	v_mul_f32_e32 v112, v112, v144
	v_mul_f32_e32 v113, v113, v162
	v_mul_f32_e32 v113, v113, v145
	v_mul_f32_e32 v114, v114, v162
	v_mul_f32_e32 v114, v114, v146
	v_mul_f32_e32 v115, v115, v162
	v_mul_f32_e32 v115, v115, v147
	v_mul_f32_e32 v116, v116, v162
	v_mul_f32_e32 v116, v116, v148
	v_mul_f32_e32 v117, v117, v162
	v_mul_f32_e32 v117, v117, v149
	v_mul_f32_e32 v118, v118, v162
	v_mul_f32_e32 v118, v118, v150
	v_mul_f32_e32 v119, v119, v162
	v_mul_f32_e32 v119, v119, v151
	v_mul_f32_e32 v120, v120, v162
	v_mul_f32_e32 v120, v120, v152
	v_mul_f32_e32 v121, v121, v162
	v_mul_f32_e32 v121, v121, v153
	v_mul_f32_e32 v122, v122, v162
	v_mul_f32_e32 v122, v122, v154
	v_mul_f32_e32 v123, v123, v162
	v_mul_f32_e32 v123, v123, v155
	v_mul_f32_e32 v124, v124, v162
	v_mul_f32_e32 v124, v124, v156
	v_mul_f32_e32 v125, v125, v162
	v_mul_f32_e32 v125, v125, v157
	v_mul_f32_e32 v126, v126, v162
	v_mul_f32_e32 v126, v126, v158
	v_mul_f32_e32 v127, v127, v162
	v_mul_f32_e32 v127, v127, v159
	global_store_dwordx4 v171, v[64:67], s[12:13]
	global_store_dwordx4 v171, v[68:71], s[12:13] offset:1024
	global_store_dwordx4 v171, v[72:75], s[12:13] offset:2048
	global_store_dwordx4 v171, v[76:79], s[12:13] offset:3072
	global_store_dwordx4 v171, v[80:83], s[14:15]
	global_store_dwordx4 v171, v[84:87], s[14:15] offset:1024
	global_store_dwordx4 v171, v[88:91], s[14:15] offset:2048
	global_store_dwordx4 v171, v[92:95], s[14:15] offset:3072
	global_store_dwordx4 v171, v[96:99], s[16:17]
	global_store_dwordx4 v171, v[100:103], s[16:17] offset:1024
	global_store_dwordx4 v171, v[104:107], s[16:17] offset:2048
	global_store_dwordx4 v171, v[108:111], s[16:17] offset:3072
	global_store_dwordx4 v171, v[112:115], s[18:19]
	global_store_dwordx4 v171, v[116:119], s[18:19] offset:1024
	global_store_dwordx4 v171, v[120:123], s[18:19] offset:2048
	global_store_dwordx4 v171, v[124:127], s[18:19] offset:3072
	s_cmp_eq_u32 s30, 0
	s_cbranch_scc1 .LBB0_886
; __device__ __forceinline__ int obid() { int t = blockIdx.x; asm volatile("" : "+s"(t)); return t; }
; __device__ __forceinline__ int ogdim() { int t = gridDim.x; asm volatile("" : "+s"(t)); return t; }
; __device__ __forceinline__ void final_norm(float* __restrict__ io, const float* __restrict__ g) {
;     ...
;     for (int row = (obid() * 8 + wid) * 2; row < NBATCH * SEQ; row += ogdim() * 16) {
;         f32x4 v[2][8];
; #pragma unroll
;         for (int q = 0; q < 2; ++q)
; #pragma unroll
;             for (int j = 0; j < 8; ++j) v[q][j] = *(const f32x4*)(io + (size_t)(row + q) * DM + j * 256 + lane * 4);
	s_mov_b32 s8, s28
	s_mov_b64 s[12:13], s[20:21]
	s_mov_b64 s[14:15], s[22:23]
	s_mov_b64 s[16:17], s[24:25]
	s_mov_b64 s[18:19], s[26:27]
	s_add_u32 s28, s8, s9
	s_cmp_lt_u32 s28, 0x8000
	s_cselect_b32 s30, 1, 0
	s_cbranch_scc0 .Lmy_fn_nonext_ia
	s_lshl_b32 s29, s28, 13
	s_add_u32 s20, s6, s29
	s_addc_u32 s21, s7, 0
	s_add_u32 s22, s20, 0x1000
	s_addc_u32 s23, s21, 0
	s_add_u32 s24, s20, 0x2000
	s_addc_u32 s25, s21, 0
	s_add_u32 s26, s20, 0x3000
	s_addc_u32 s27, s21, 0
	global_load_dwordx4 v[64:67], v171, s[20:21]
	global_load_dwordx4 v[68:71], v171, s[20:21] offset:1024
	global_load_dwordx4 v[72:75], v171, s[20:21] offset:2048
	global_load_dwordx4 v[76:79], v171, s[20:21] offset:3072
	global_load_dwordx4 v[80:83], v171, s[22:23]
	global_load_dwordx4 v[84:87], v171, s[22:23] offset:1024
	global_load_dwordx4 v[88:91], v171, s[22:23] offset:2048
	global_load_dwordx4 v[92:95], v171, s[22:23] offset:3072
	global_load_dwordx4 v[96:99], v171, s[24:25]
	global_load_dwordx4 v[100:103], v171, s[24:25] offset:1024
	global_load_dwordx4 v[104:107], v171, s[24:25] offset:2048
	global_load_dwordx4 v[108:111], v171, s[24:25] offset:3072
	global_load_dwordx4 v[112:115], v171, s[26:27]
	global_load_dwordx4 v[116:119], v171, s[26:27] offset:1024
	global_load_dwordx4 v[120:123], v171, s[26:27] offset:2048
	global_load_dwordx4 v[124:127], v171, s[26:27] offset:3072
	s_waitcnt vmcnt(32)
	s_branch .Lmy_fn_proc_ia

; __device__ __forceinline__ void final_norm(float* __restrict__ io, const float* __restrict__ g) {
;     ...
;         for (int q = 0; q < 2; ++q) { float ss = 0.f;
; #pragma unroll
;             for (int j = 0; j < 8; ++j) ss += v[q][j][0] * v[q][j][0] + v[q][j][1] * v[q][j][1] + v[q][j][2] * v[q][j][2] + v[q][j][3] * v[q][j][3];
;             ss = wave_sum(ss); const float rs = rsqrtf(ss * (1.f / DM) + EPS);
.Lmy_fn_proc_ia:
	v_mul_f32_e32 v161, v0, v0
	v_fmac_f32_e32 v161, v1, v1
	v_fmac_f32_e32 v161, v2, v2
	v_fmac_f32_e32 v161, v3, v3
	v_fmac_f32_e32 v161, v4, v4
	v_fmac_f32_e32 v161, v5, v5
	v_fmac_f32_e32 v161, v6, v6
	v_fmac_f32_e32 v161, v7, v7
	v_fmac_f32_e32 v161, v8, v8
	v_fmac_f32_e32 v161, v9, v9
	v_fmac_f32_e32 v161, v10, v10
	v_fmac_f32_e32 v161, v11, v11
	v_fmac_f32_e32 v161, v12, v12
	v_fmac_f32_e32 v161, v13, v13
	v_fmac_f32_e32 v161, v14, v14
	v_fmac_f32_e32 v161, v15, v15
	v_fmac_f32_e32 v161, v16, v16
	v_fmac_f32_e32 v161, v17, v17
	v_fmac_f32_e32 v161, v18, v18
	v_fmac_f32_e32 v161, v19, v19
	v_fmac_f32_e32 v161, v20, v20
	v_fmac_f32_e32 v161, v21, v21
	v_fmac_f32_e32 v161, v22, v22
	v_fmac_f32_e32 v161, v23, v23
	v_fmac_f32_e32 v161, v24, v24
	v_fmac_f32_e32 v161, v25, v25
	v_fmac_f32_e32 v161, v26, v26
	v_fmac_f32_e32 v161, v27, v27
	v_fmac_f32_e32 v161, v28, v28
	v_fmac_f32_e32 v161, v29, v29
	v_fmac_f32_e32 v161, v30, v30
	v_fmac_f32_e32 v161, v31, v31
	v_mul_f32_e32 v162, v32, v32
	v_fmac_f32_e32 v162, v33, v33
	v_fmac_f32_e32 v162, v34, v34
	v_fmac_f32_e32 v162, v35, v35
	v_fmac_f32_e32 v162, v36, v36
	v_fmac_f32_e32 v162, v37, v37
	v_fmac_f32_e32 v162, v38, v38
	v_fmac_f32_e32 v162, v39, v39
	v_fmac_f32_e32 v162, v40, v40
	v_fmac_f32_e32 v162, v41, v41
	v_fmac_f32_e32 v162, v42, v42
	v_fmac_f32_e32 v162, v43, v43
	v_fmac_f32_e32 v162, v44, v44
	v_fmac_f32_e32 v162, v45, v45
	v_fmac_f32_e32 v162, v46, v46
	v_fmac_f32_e32 v162, v47, v47
	v_fmac_f32_e32 v162, v48, v48
	v_fmac_f32_e32 v162, v49, v49
	v_fmac_f32_e32 v162, v50, v50
	v_fmac_f32_e32 v162, v51, v51
	v_fmac_f32_e32 v162, v52, v52
	v_fmac_f32_e32 v162, v53, v53
	v_fmac_f32_e32 v162, v54, v54
	v_fmac_f32_e32 v162, v55, v55
	v_fmac_f32_e32 v162, v56, v56
	v_fmac_f32_e32 v162, v57, v57
	v_fmac_f32_e32 v162, v58, v58
	v_fmac_f32_e32 v162, v59, v59
	v_fmac_f32_e32 v162, v60, v60
	v_fmac_f32_e32 v162, v61, v61
	v_fmac_f32_e32 v162, v62, v62
	v_fmac_f32_e32 v162, v63, v63
	ds_bpermute_b32 v163, v172, v161
	ds_bpermute_b32 v164, v172, v162
	s_waitcnt lgkmcnt(0)
	v_add_f32_e32 v161, v161, v163
	v_add_f32_e32 v162, v162, v164
	ds_bpermute_b32 v163, v173, v161
	ds_bpermute_b32 v164, v173, v162
	s_waitcnt lgkmcnt(0)
	v_add_f32_e32 v161, v161, v163
	v_add_f32_e32 v162, v162, v164
	ds_bpermute_b32 v163, v174, v161
	ds_bpermute_b32 v164, v174, v162
	s_waitcnt lgkmcnt(0)
	v_add_f32_e32 v161, v161, v163
	v_add_f32_e32 v162, v162, v164
	ds_bpermute_b32 v163, v175, v161
	ds_bpermute_b32 v164, v175, v162
	s_waitcnt lgkmcnt(0)
	v_add_f32_e32 v161, v161, v163
	v_add_f32_e32 v162, v162, v164
	ds_bpermute_b32 v163, v176, v161
	ds_bpermute_b32 v164, v176, v162
	s_waitcnt lgkmcnt(0)
	v_add_f32_e32 v161, v161, v163
	v_add_f32_e32 v162, v162, v164
	ds_bpermute_b32 v163, v177, v161
	ds_bpermute_b32 v164, v177, v162
	s_waitcnt lgkmcnt(0)
; __device__ __forceinline__ void final_norm(float* __restrict__ io, const float* __restrict__ g) {
;     ...
;             ss = wave_sum(ss); const float rs = rsqrtf(ss * (1.f / DM) + EPS);
; #pragma unroll
;             for (int j = 0; j < 8; ++j) *(f32x4*)(io + (size_t)(row + q) * DM + j * 256 + lane * 4) = v[q][j] * rs * gg[j]; }
	v_add_f32_e32 v161, v161, v163
	v_add_f32_e32 v162, v162, v164
	v_fmamk_f32 v161, v161, 0x3a000000, v160
	v_fmamk_f32 v162, v162, 0x3a000000, v160
	v_rsq_f32_e32 v161, v161
	v_rsq_f32_e32 v162, v162
	s_nop 1
	v_mul_f32_e32 v0, v0, v161
	v_mul_f32_e32 v0, v0, v128
	v_mul_f32_e32 v1, v1, v161
	v_mul_f32_e32 v1, v1, v129
	v_mul_f32_e32 v2, v2, v161
	v_mul_f32_e32 v2, v2, v130
	v_mul_f32_e32 v3, v3, v161
	v_mul_f32_e32 v3, v3, v131
	v_mul_f32_e32 v4, v4, v161
	v_mul_f32_e32 v4, v4, v132
	v_mul_f32_e32 v5, v5, v161
	v_mul_f32_e32 v5, v5, v133
	v_mul_f32_e32 v6, v6, v161
	v_mul_f32_e32 v6, v6, v134
	v_mul_f32_e32 v7, v7, v161
	v_mul_f32_e32 v7, v7, v135
	v_mul_f32_e32 v8, v8, v161
	v_mul_f32_e32 v8, v8, v136
	v_mul_f32_e32 v9, v9, v161
	v_mul_f32_e32 v9, v9, v137
	v_mul_f32_e32 v10, v10, v161
	v_mul_f32_e32 v10, v10, v138
	v_mul_f32_e32 v11, v11, v161
	v_mul_f32_e32 v11, v11, v139
	v_mul_f32_e32 v12, v12, v161
	v_mul_f32_e32 v12, v12, v140
	v_mul_f32_e32 v13, v13, v161
	v_mul_f32_e32 v13, v13, v141
	v_mul_f32_e32 v14, v14, v161
	v_mul_f32_e32 v14, v14, v142
	v_mul_f32_e32 v15, v15, v161
	v_mul_f32_e32 v15, v15, v143
	v_mul_f32_e32 v16, v16, v161
	v_mul_f32_e32 v16, v16, v144
	v_mul_f32_e32 v17, v17, v161
	v_mul_f32_e32 v17, v17, v145
	v_mul_f32_e32 v18, v18, v161
	v_mul_f32_e32 v18, v18, v146
	v_mul_f32_e32 v19, v19, v161
	v_mul_f32_e32 v19, v19, v147
	v_mul_f32_e32 v20, v20, v161
	v_mul_f32_e32 v20, v20, v148
	v_mul_f32_e32 v21, v21, v161
	v_mul_f32_e32 v21, v21, v149
	v_mul_f32_e32 v22, v22, v161
	v_mul_f32_e32 v22, v22, v150
	v_mul_f32_e32 v23, v23, v161
	v_mul_f32_e32 v23, v23, v151
	v_mul_f32_e32 v24, v24, v161
	v_mul_f32_e32 v24, v24, v152
	v_mul_f32_e32 v25, v25, v161
	v_mul_f32_e32 v25, v25, v153
	v_mul_f32_e32 v26, v26, v161
	v_mul_f32_e32 v26, v26, v154
	v_mul_f32_e32 v27, v27, v161
	v_mul_f32_e32 v27, v27, v155
	v_mul_f32_e32 v28, v28, v161
	v_mul_f32_e32 v28, v28, v156
	v_mul_f32_e32 v29, v29, v161
	v_mul_f32_e32 v29, v29, v157
	v_mul_f32_e32 v30, v30, v161
	v_mul_f32_e32 v30, v30, v158
	v_mul_f32_e32 v31, v31, v161
	v_mul_f32_e32 v31, v31, v159
	v_mul_f32_e32 v32, v32, v162
	v_mul_f32_e32 v32, v32, v128
	v_mul_f32_e32 v33, v33, v162
	v_mul_f32_e32 v33, v33, v129
	v_mul_f32_e32 v34, v34, v162
	v_mul_f32_e32 v34, v34, v130
	v_mul_f32_e32 v35, v35, v162
	v_mul_f32_e32 v35, v35, v131
	v_mul_f32_e32 v36, v36, v162
	v_mul_f32_e32 v36, v36, v132
	v_mul_f32_e32 v37, v37, v162
	v_mul_f32_e32 v37, v37, v133
	v_mul_f32_e32 v38, v38, v162
	v_mul_f32_e32 v38, v38, v134
	v_mul_f32_e32 v39, v39, v162
	v_mul_f32_e32 v39, v39, v135
	v_mul_f32_e32 v40, v40, v162
	v_mul_f32_e32 v40, v40, v136
	v_mul_f32_e32 v41, v41, v162
	v_mul_f32_e32 v41, v41, v137
	v_mul_f32_e32 v42, v42, v162
	v_mul_f32_e32 v42, v42, v138
	v_mul_f32_e32 v43, v43, v162
	v_mul_f32_e32 v43, v43, v139
	v_mul_f32_e32 v44, v44, v162
	v_mul_f32_e32 v44, v44, v140
	v_mul_f32_e32 v45, v45, v162
	v_mul_f32_e32 v45, v45, v141
	v_mul_f32_e32 v46, v46, v162
	v_mul_f32_e32 v46, v46, v142
	v_mul_f32_e32 v47, v47, v162
	v_mul_f32_e32 v47, v47, v143
	v_mul_f32_e32 v48, v48, v162
	v_mul_f32_e32 v48, v48, v144
	v_mul_f32_e32 v49, v49, v162
	v_mul_f32_e32 v49, v49, v145
	v_mul_f32_e32 v50, v50, v162
	v_mul_f32_e32 v50, v50, v146
	v_mul_f32_e32 v51, v51, v162
	v_mul_f32_e32 v51, v51, v147
	v_mul_f32_e32 v52, v52, v162
	v_mul_f32_e32 v52, v52, v148
	v_mul_f32_e32 v53, v53, v162
	v_mul_f32_e32 v53, v53, v149
	v_mul_f32_e32 v54, v54, v162
	v_mul_f32_e32 v54, v54, v150
	v_mul_f32_e32 v55, v55, v162
	v_mul_f32_e32 v55, v55, v151
	v_mul_f32_e32 v56, v56, v162
	v_mul_f32_e32 v56, v56, v152
	v_mul_f32_e32 v57, v57, v162
	v_mul_f32_e32 v57, v57, v153
	v_mul_f32_e32 v58, v58, v162
	v_mul_f32_e32 v58, v58, v154
	v_mul_f32_e32 v59, v59, v162
	v_mul_f32_e32 v59, v59, v155
	v_mul_f32_e32 v60, v60, v162
	v_mul_f32_e32 v60, v60, v156
	v_mul_f32_e32 v61, v61, v162
	v_mul_f32_e32 v61, v61, v157
	v_mul_f32_e32 v62, v62, v162
	v_mul_f32_e32 v62, v62, v158
	v_mul_f32_e32 v63, v63, v162
	v_mul_f32_e32 v63, v63, v159
	global_store_dwordx4 v171, v[0:3], s[12:13]
	global_store_dwordx4 v171, v[4:7], s[12:13] offset:1024
	global_store_dwordx4 v171, v[8:11], s[12:13] offset:2048
	global_store_dwordx4 v171, v[12:15], s[12:13] offset:3072
	global_store_dwordx4 v171, v[16:19], s[14:15]
	global_store_dwordx4 v171, v[20:23], s[14:15] offset:1024
	global_store_dwordx4 v171, v[24:27], s[14:15] offset:2048
	global_store_dwordx4 v171, v[28:31], s[14:15] offset:3072
	global_store_dwordx4 v171, v[32:35], s[16:17]
	global_store_dwordx4 v171, v[36:39], s[16:17] offset:1024
	global_store_dwordx4 v171, v[40:43], s[16:17] offset:2048
	global_store_dwordx4 v171, v[44:47], s[16:17] offset:3072
	global_store_dwordx4 v171, v[48:51], s[18:19]
	global_store_dwordx4 v171, v[52:55], s[18:19] offset:1024
	global_store_dwordx4 v171, v[56:59], s[18:19] offset:2048
	global_store_dwordx4 v171, v[60:63], s[18:19] offset:3072
	s_cmp_eq_u32 s30, 0
	s_cbranch_scc1 .LBB0_886
	s_mov_b32 s8, s28
	s_mov_b64 s[12:13], s[20:21]
	s_mov_b64 s[14:15], s[22:23]
	s_mov_b64 s[16:17], s[24:25]
	s_mov_b64 s[18:19], s[26:27]
	s_branch .Lmy_fn_loop
